# c3 stage-2 and c1 second-half MFMA sections: LDS fragment reads batched and double-buffered (one exposed LDS latency per K step instead of one per MFMA)
# speedup vs baseline: 1.0875x; 1.0050x over previous
; #define LAS __attribute__((address_space(3)))
; __device__ __forceinline__ bf16_t f2bf(float f) { return (bf16_t)(cvt_pk_bf16(f, 0.f) & 0xffffu); }
; __device__ __forceinline__ void phase_hgrn_c3(const Params& p, int l, int bid, int nblk, LAS unsigned char* lds) {
;     ...
;             for (int j = 0; j < 4; ++j) { const int t = 16 * tt + (lane >> 4) * 4 + j, s = 16 * st + (lane & 15); at[t * 72 + s] = f2bf(s <= t ? a4[j] : 0.f); }
;         }
;         __syncthreads();
;         f32x4 acc[4];
; #pragma unroll
;         for (int vt = 0; vt < 4; ++vt) acc[vt] = (f32x4){0.f, 0.f, 0.f, 0.f};
; #pragma unroll
;         for (int ks = 0; ks < 4; ++ks) {
;             const bf16x8 af = *(const LAS bf16x8*)(qB + (16 * tt + (lane & 15)) * 136 + ks * 32 + (lane >> 4) * 8);
; #pragma unroll
;             for (int vt = 0; vt < 4; ++vt) {
;                 const bf16x8 bfr = *(const LAS bf16x8*)(S0T + (16 * (vh * 4 + vt) + (lane & 15)) * 136 + ks * 32 + (lane >> 4) * 8);
;                 acc[vt] = __builtin_amdgcn_mfma_f32_16x16x32_bf16(af, bfr, acc[vt], 0, 0, 0);
;             }
;         }
; #pragma unroll
;         for (int ks = 0; ks < 2; ++ks) {
;             const bf16x8 af = *(const LAS bf16x8*)(at + (16 * tt + (lane & 15)) * 72 + ks * 32 + (lane >> 4) * 8);
; #pragma unroll
;             for (int vt = 0; vt < 4; ++vt) {
;                 const bf16x8 bfr = *(const LAS bf16x8*)(vT + (16 * (vh * 4 + vt) + (lane & 15)) * 72 + ks * 32 + (lane >> 4) * 8);
;                 acc[vt] = __builtin_amdgcn_mfma_f32_16x16x32_bf16(af, bfr, acc[vt], 0, 0, 0);
;             }
;         }
; #pragma unroll
;         for (int j = 0; j < 4; ++j) {
;             float s2 = 0.f;
; #pragma unroll
;             for (int vt = 0; vt < 4; ++vt) s2 += acc[vt][j] * acc[vt][j];
;             s2 += __shfl_xor(s2, 1); s2 += __shfl_xor(s2, 2); s2 += __shfl_xor(s2, 4); s2 += __shfl_xor(s2, 8);
;             if ((lane & 15) == 0) ssq[vh * 64 + 16 * tt + (lane >> 4) * 4 + j] = s2;
.LBB0_249:
	s_or_b64 exec, exec, s[38:39]
	s_nop 6
	v_cndmask_b32_e64 v26, v26, 0, s[26:27]
	v_cvt_pk_bf16_f32 v26, v26, v5
	ds_write_b16 v115, v26
	v_cndmask_b32_e64 v26, v27, 0, s[28:29]
	v_cvt_pk_bf16_f32 v26, v26, v5
	ds_write_b16 v116, v26
	v_cndmask_b32_e64 v26, v28, 0, s[30:31]
	v_cvt_pk_bf16_f32 v26, v26, v5
	ds_write_b16 v117, v26
	v_cndmask_b32_e64 v26, v29, 0, s[34:35]
	v_cvt_pk_bf16_f32 v26, v26, v5
	ds_write_b16 v118, v26
	s_waitcnt lgkmcnt(0)
	s_barrier
	v_and_b32_e32 v67, 64, v240
	v_xor_b32_e32 v63, 1, v240
	ds_read_b128 v[188:191], v47 offset:17408
	ds_read_b128 v[192:195], v128 offset:52224
	ds_read_b128 v[196:199], v128 offset:56576
	ds_read_b128 v[200:203], v128 offset:60928
	ds_read_b128 v[204:207], v128 offset:65280
	ds_read_b128 v[208:211], v47 offset:17472
	ds_read_b128 v[212:215], v128 offset:52288
	ds_read_b128 v[216:219], v128 offset:56640
	ds_read_b128 v[220:223], v128 offset:60992
	ds_read_b128 v[224:227], v128 offset:65344
	s_waitcnt lgkmcnt(5)
	v_mfma_f32_16x16x32_bf16 v[38:41], v[188:191], v[192:195], 0
	v_mfma_f32_16x16x32_bf16 v[34:37], v[188:191], v[196:199], 0
	v_mfma_f32_16x16x32_bf16 v[30:33], v[188:191], v[200:203], 0
	v_mfma_f32_16x16x32_bf16 v[26:29], v[188:191], v[204:207], 0
	s_nop 3
	ds_read_b128 v[188:191], v47 offset:17536
	ds_read_b128 v[192:195], v128 offset:52352
	ds_read_b128 v[196:199], v128 offset:56704
	ds_read_b128 v[200:203], v128 offset:61056
	ds_read_b128 v[204:207], v128 offset:65408
	s_waitcnt lgkmcnt(5)
	v_mfma_f32_16x16x32_bf16 v[38:41], v[208:211], v[212:215], v[38:41]
	v_mfma_f32_16x16x32_bf16 v[34:37], v[208:211], v[216:219], v[34:37]
	v_mfma_f32_16x16x32_bf16 v[30:33], v[208:211], v[220:223], v[30:33]
	v_mfma_f32_16x16x32_bf16 v[26:29], v[208:211], v[224:227], v[26:29]
	s_nop 3
	ds_read_b128 v[208:211], v47 offset:17600
	ds_read_b128 v[212:215], v128 offset:52416
	ds_read_b128 v[216:219], v128 offset:56768
	ds_read_b128 v[220:223], v128 offset:61120
	ds_read_b128 v[224:227], v128 offset:65472
	s_waitcnt lgkmcnt(5)
	v_mfma_f32_16x16x32_bf16 v[38:41], v[188:191], v[192:195], v[38:41]
	v_mfma_f32_16x16x32_bf16 v[34:37], v[188:191], v[196:199], v[34:37]
	v_mfma_f32_16x16x32_bf16 v[30:33], v[188:191], v[200:203], v[30:33]
	v_mfma_f32_16x16x32_bf16 v[26:29], v[188:191], v[204:207], v[26:29]
	s_nop 3
	ds_read_b128 v[188:191], v106
	ds_read_b128 v[192:195], v129
	ds_read_b128 v[196:199], v129 offset:2304
	ds_read_b128 v[200:203], v129 offset:4608
	ds_read_b128 v[204:207], v129 offset:6912
	s_waitcnt lgkmcnt(5)
	v_mfma_f32_16x16x32_bf16 v[38:41], v[208:211], v[212:215], v[38:41]
	v_mfma_f32_16x16x32_bf16 v[34:37], v[208:211], v[216:219], v[34:37]
	v_mfma_f32_16x16x32_bf16 v[30:33], v[208:211], v[220:223], v[30:33]
	v_mfma_f32_16x16x32_bf16 v[26:29], v[208:211], v[224:227], v[26:29]
	s_nop 3
	ds_read_b128 v[208:211], v106 offset:64
	ds_read_b128 v[212:215], v129 offset:64
	ds_read_b128 v[216:219], v129 offset:2368
	ds_read_b128 v[220:223], v129 offset:4672
	ds_read_b128 v[224:227], v129 offset:6976
	s_waitcnt lgkmcnt(5)
	v_mfma_f32_16x16x32_bf16 v[38:41], v[188:191], v[192:195], v[38:41]
	v_mfma_f32_16x16x32_bf16 v[34:37], v[188:191], v[196:199], v[34:37]
	v_mfma_f32_16x16x32_bf16 v[30:33], v[188:191], v[200:203], v[30:33]
	v_mfma_f32_16x16x32_bf16 v[26:29], v[188:191], v[204:207], v[26:29]
	s_waitcnt lgkmcnt(0)
	v_mfma_f32_16x16x32_bf16 v[38:41], v[208:211], v[212:215], v[38:41]
	v_mfma_f32_16x16x32_bf16 v[34:37], v[208:211], v[216:219], v[34:37]
	v_mfma_f32_16x16x32_bf16 v[30:33], v[208:211], v[220:223], v[30:33]
	v_mfma_f32_16x16x32_bf16 v[26:29], v[208:211], v[224:227], v[26:29]
	v_add_u32_e32 v149, 64, v67
	v_cmp_lt_i32_e32 vcc, v63, v149
	v_xor_b32_e32 v67, 2, v240
	v_xor_b32_e32 v148, 4, v240
	v_cndmask_b32_e32 v63, v240, v63, vcc
	v_cmp_lt_i32_e32 vcc, v67, v149
	v_xor_b32_e32 v150, 8, v240
	v_lshlrev_b32_e32 v63, 2, v63
	v_cndmask_b32_e32 v67, v240, v67, vcc
	v_cmp_lt_i32_e32 vcc, v148, v149
	v_lshlrev_b32_e32 v67, 2, v67
	s_nop 0
	v_cndmask_b32_e32 v148, v240, v148, vcc
	v_cmp_lt_i32_e32 vcc, v150, v149
	v_lshlrev_b32_e32 v148, 2, v148
	s_nop 0
	v_cndmask_b32_e32 v149, v240, v150, vcc
	v_mul_f32_e32 v150, v34, v34
	v_fmac_f32_e32 v150, v38, v38
	v_fmac_f32_e32 v150, v30, v30
	v_fmac_f32_e32 v150, v26, v26
	ds_bpermute_b32 v151, v63, v150
	v_lshlrev_b32_e32 v149, 2, v149
	s_waitcnt lgkmcnt(0)
	v_add_f32_e32 v150, v150, v151
	ds_bpermute_b32 v151, v67, v150
	s_waitcnt lgkmcnt(0)
	v_add_f32_e32 v150, v150, v151
	ds_bpermute_b32 v151, v148, v150
	s_waitcnt lgkmcnt(0)
	v_add_f32_e32 v150, v150, v151
	ds_bpermute_b32 v151, v149, v150
	s_and_saveexec_b64 s[38:39], s[4:5]
	s_cbranch_execz .LBB0_251
	s_waitcnt lgkmcnt(0)
	v_add_f32_e32 v150, v150, v151
	ds_write_b32 v131, v150

; #define LAS __attribute__((address_space(3)))
; __device__ __forceinline__ void phase_hgrn_c1(const Params& p, int l, int bid, int nblk, LAS unsigned char* lds) {
;     ...
;         f32x4 acc[8];
; #pragma unroll
;         for (int vt = 0; vt < 8; ++vt) acc[vt] = (f32x4){0.f, 0.f, 0.f, 0.f};
; #pragma unroll
;         for (int ks = 0; ks < 2; ++ks) {
;             const bf16x8 af = *(const LAS bf16x8*)(kT + (16 * wid + (lane & 15)) * 72 + ks * 32 + (lane >> 4) * 8);
; #pragma unroll
;             for (int vt = 0; vt < 8; ++vt) {
;                 const bf16x8 bfr = *(const LAS bf16x8*)(vT + (16 * vt + (lane & 15)) * 72 + ks * 32 + (lane >> 4) * 8);
;                 acc[vt] = __builtin_amdgcn_mfma_f32_16x16x32_bf16(af, bfr, acc[vt], 0, 0, 0);
;             }
;         }
;         float* gst = p.Gst + (size_t)(c * 8 + h) * 16384;
; #pragma unroll
;         for (int vt = 0; vt < 8; ++vt) *(f32x4*)(gst + (16 * vt + (lane & 15)) * 128 + 16 * wid + (lane >> 4) * 4) = acc[vt];
;         __syncthreads();
.LBB0_409:
	s_or_b64 exec, exec, s[28:29]
	s_waitcnt lgkmcnt(0)
	s_barrier
	ds_read_b128 v[22:25], v18
	ds_read_b128 v[52:55], v43 offset:18432
	ds_read_b128 v[56:59], v43 offset:20736
	ds_read_b128 v[80:83], v43 offset:34560
	ds_read_b128 v[60:63], v43 offset:23040
	ds_read_b128 v[64:67], v43 offset:25344
	ds_read_b128 v[68:71], v43 offset:27648
	ds_read_b128 v[72:75], v43 offset:29952
	ds_read_b128 v[76:79], v43 offset:32256
	s_waitcnt lgkmcnt(7)
	v_mfma_f32_16x16x32_bf16 v[52:55], v[22:25], v[52:55], 0
	s_lshl_b64 s[46:47], s[50:51], 16
	v_mov_b32_e32 v21, v5
	s_mov_b32 s50, s44
	s_waitcnt lgkmcnt(6)
	v_mfma_f32_16x16x32_bf16 v[56:59], v[22:25], v[56:59], 0
	s_waitcnt lgkmcnt(4)
	v_mfma_f32_16x16x32_bf16 v[60:63], v[22:25], v[60:63], 0
	s_waitcnt lgkmcnt(3)
	v_mfma_f32_16x16x32_bf16 v[64:67], v[22:25], v[64:67], 0
	s_waitcnt lgkmcnt(2)
	v_mfma_f32_16x16x32_bf16 v[68:71], v[22:25], v[68:71], 0
	s_waitcnt lgkmcnt(1)
	v_mfma_f32_16x16x32_bf16 v[72:75], v[22:25], v[72:75], 0
	s_waitcnt lgkmcnt(0)
	v_mfma_f32_16x16x32_bf16 v[76:79], v[22:25], v[76:79], 0
	v_mfma_f32_16x16x32_bf16 v[22:25], v[22:25], v[80:83], 0
	ds_read_b128 v[80:83], v18 offset:64
	ds_read_b128 v[84:87], v43 offset:18496
	ds_read_b128 v[88:91], v43 offset:20800
	ds_read_b128 v[92:95], v43 offset:23104
	ds_read_b128 v[96:99], v43 offset:25408
	ds_read_b128 v[100:103], v43 offset:27712
	ds_read_b128 v[104:107], v43 offset:30016
	ds_read_b128 v[108:111], v43 offset:32320
	ds_read_b128 v[112:115], v43 offset:34624
	s_load_dwordx2 s[28:29], s[0:1], 0x120
	s_addk_i32 s38, 0xe0
	s_add_i32 s39, s39, s42
	s_add_i32 s34, s34, 1
	s_waitcnt lgkmcnt(0)
	s_add_u32 s28, s28, s46
	s_addc_u32 s29, s29, s47
	v_mfma_f32_16x16x32_bf16 v[52:55], v[80:83], v[84:87], v[52:55]
	v_mfma_f32_16x16x32_bf16 v[56:59], v[80:83], v[88:91], v[56:59]
	v_mfma_f32_16x16x32_bf16 v[60:63], v[80:83], v[92:95], v[60:63]
	v_mfma_f32_16x16x32_bf16 v[64:67], v[80:83], v[96:99], v[64:67]
	v_mfma_f32_16x16x32_bf16 v[68:71], v[80:83], v[100:103], v[68:71]
	v_mfma_f32_16x16x32_bf16 v[72:75], v[80:83], v[104:107], v[72:75]
	v_mfma_f32_16x16x32_bf16 v[76:79], v[80:83], v[108:111], v[76:79]
	v_mfma_f32_16x16x32_bf16 v[22:25], v[80:83], v[112:115], v[22:25]
	v_lshl_add_u64 v[80:81], v[16:17], 2, s[28:29]
	v_lshl_add_u64 v[80:81], v[80:81], 0, v[4:5]
	v_lshl_add_u64 v[80:81], v[80:81], 0, v[20:21]
	global_store_dwordx4 v[80:81], v[52:55], off
	s_movk_i32 s28, 0x6000
	s_nop 0
	v_add_co_u32_e32 v52, vcc, s59, v80
	s_nop 1
	v_addc_co_u32_e32 v53, vcc, 0, v81, vcc
	global_store_dwordx4 v[52:53], v[56:59], off
	v_add_co_u32_e32 v52, vcc, s48, v80
	s_nop 1
	v_addc_co_u32_e32 v53, vcc, 0, v81, vcc
	global_store_dwordx4 v[52:53], v[60:63], off
	v_add_co_u32_e32 v52, vcc, s28, v80
	s_mov_b32 s28, 0x8000
	s_nop 0
	v_addc_co_u32_e32 v53, vcc, 0, v81, vcc
	global_store_dwordx4 v[52:53], v[64:67], off
	v_add_co_u32_e32 v52, vcc, s28, v80
	s_mov_b32 s28, 0xa000
	s_nop 0
	v_addc_co_u32_e32 v53, vcc, 0, v81, vcc
	global_store_dwordx4 v[52:53], v[68:71], off
	v_add_co_u32_e32 v52, vcc, s28, v80
	s_mov_b32 s28, 0xc000
	s_nop 0
	v_addc_co_u32_e32 v53, vcc, 0, v81, vcc
	global_store_dwordx4 v[52:53], v[72:75], off
	v_add_co_u32_e32 v52, vcc, s28, v80
	s_nop 1
	v_addc_co_u32_e32 v53, vcc, 0, v81, vcc
	global_store_dwordx4 v[52:53], v[76:79], off
	v_add_co_u32_e32 v52, vcc, 0xe000, v80
	s_nop 1
	v_addc_co_u32_e32 v53, vcc, 0, v81, vcc
	s_andn2_b64 vcc, exec, s[14:15]
	global_store_dwordx4 v[52:53], v[22:25], off
	s_barrier
	s_cbranch_vccz .LBB0_427
